# c18 + attention: next-item queue atomic issued before the item's output stores (counted wait), so the fetch no longer waits for the store acks
# speedup vs baseline: 1.0020x; 1.0020x over previous
.LBB0_806:
	s_mov_b32 s94, 0
	v_readlane_b32 s81, v254, 44
	s_and_b32 s49, s81, 7
	s_lshl_b32 s0, s49, 2
	s_add_u32 s12, s78, s0
	s_addc_u32 s13, s79, 0
	s_lshl_b32 s0, s49, 4
	s_or_b32 s50, s0, 0x380
	s_add_u32 s51, s78, 0xa81000
	s_addc_u32 s52, s79, 0
	s_add_u32 s53, s78, 0xb81000
	s_addc_u32 s54, s79, 0
	s_add_u32 s55, s76, 0x8100000
	s_addc_u32 s56, s77, 0
	s_add_u32 s57, s76, 0xc100000
	s_addc_u32 s58, s77, 0
	s_add_u32 s59, s76, 0x10243500
	s_addc_u32 s60, s77, 0
	v_readlane_b32 s0, v254, 42
	s_add_u32 s61, s76, 0x102c3500
	v_readlane_b32 s1, v254, 43
	s_addc_u32 s62, s77, 0
	s_add_u32 s14, s78, 0x126f1000
	s_waitcnt vmcnt(3)
	v_cndmask_b32_e64 v0, 0, 1, s[0:1]
	v_cmp_ne_u32_e64 s[2:3], 1, v0
	v_mbcnt_lo_u32_b32 v0, -1, 0
	s_addc_u32 s15, s79, 0
	s_lshl_b32 s63, s80, 5
	v_mbcnt_hi_u32_b32 v104, -1, v0
	s_add_u32 s16, s78, 0xe671000
	v_and_b32_e32 v0, 64, v104
	s_mov_b32 s11, 0
	s_addc_u32 s17, s79, 0
	s_sub_i32 s64, s48, 64
	v_mov_b32_e32 v97, 0
	v_mov_b32_e32 v102, 0x25200
	s_movk_i32 s65, 0x7ff
	v_mov_b32_e32 v103, 0x260
	s_mov_b32 s66, 0xc1f00000
	v_xor_b32_e32 v105, 32, v104
	v_add_u32_e32 v106, 64, v0
	v_mov_b32_e32 v107, 0xff800000
	s_branch .LBB0_809

.LBB0_809:
	s_and_b64 vcc, exec, s[2:3]
	s_barrier
	s_cbranch_vccnz .LBB0_815
	s_cmp_eq_u32 s94, 0
	s_cbranch_scc1 .Laq_orig
	s_waitcnt vmcnt(8)
	v_readfirstlane_b32 s4, v153
	s_nop 1
	v_mov_b32_e32 v0, s4
	ds_write_b32 v102, v0
	s_branch .LBB0_815
.Laq_orig:
	v_mbcnt_lo_u32_b32 v0, -1, 0
	v_mbcnt_hi_u32_b32 v0, -1, v0
	s_nop 0
	v_cmp_eq_u32_e32 vcc, 0, v0
	s_and_saveexec_b64 s[0:1], vcc
	s_cbranch_execz .LBB0_814
	s_mov_b64 s[6:7], exec
	v_mbcnt_lo_u32_b32 v0, s6, 0
	v_mbcnt_hi_u32_b32 v0, s7, v0
	v_cmp_eq_u32_e32 vcc, 0, v0
	s_and_saveexec_b64 s[4:5], vcc
	s_cbranch_execz .LBB0_813
	s_bcnt1_i32_b64 s6, s[6:7]
	v_mov_b32_e32 v1, s6
	global_atomic_add v1, v97, v1, s[12:13] offset:64 sc0

.LBB0_853:
	s_mov_b32 s94, 1
	s_and_b64 vcc, exec, s[2:3]
	s_cbranch_vccnz .Laq_skip
	v_mbcnt_lo_u32_b32 v152, -1, 0
	v_mbcnt_hi_u32_b32 v152, -1, v152
	v_cmp_eq_u32_e32 vcc, 0, v152
	s_and_saveexec_b64 s[92:93], vcc
	v_mov_b32_e32 v153, 1
	global_atomic_add v153, v97, v153, s[12:13] offset:64 sc0
	s_or_b64 exec, exec, s[92:93]
